# previous stack + row-statistics butterflies in P2 q/k, P4 (x2), P8 epilogues: ds_bpermute round trips replaced by v_permlane16/32_swap (bit-identical sums)
# speedup vs baseline: 1.0144x; 1.0010x over previous
.LBB0_241:
	s_andn2_b64 vcc, exec, s[8:9]
	v_readlane_b32 s92, v255, 13
	s_cbranch_vccnz .LBB0_427
	v_mul_f32_e32 v132, v127, v127
	v_mul_f32_e32 v133, v129, v129
	v_fmac_f32_e32 v132, v126, v126
	v_fmac_f32_e32 v133, v128, v128
	v_and_b32_e32 v131, 64, v175
	v_add_f32_e32 v132, v132, v133
	v_mul_f32_e32 v133, v123, v123
	v_xor_b32_e32 v130, 16, v175
	v_add_u32_e32 v131, 64, v131
	v_fmac_f32_e32 v133, v122, v122
	v_cmp_lt_i32_e32 vcc, v130, v131
	v_add_f32_e32 v132, v132, v133
	v_mul_f32_e32 v133, v125, v125
	v_cndmask_b32_e32 v130, v175, v130, vcc
	v_fmac_f32_e32 v133, v124, v124
	v_lshlrev_b32_e32 v130, 2, v130
	v_add_f32_e32 v132, v133, v132
	v_mov_b32_e32 v133, v132
	s_nop 1
	v_permlane16_swap_b32_e32 v132, v133
	v_xor_b32_e32 v134, 32, v175
	v_cmp_lt_i32_e32 vcc, v134, v131
	s_nop 1
	v_cndmask_b32_e32 v131, v175, v134, vcc
	v_lshlrev_b32_e32 v131, 2, v131
	s_waitcnt lgkmcnt(0)
	v_add_f32_e32 v134, v132, v133
	v_mov_b32_e32 v135, v134
	s_nop 1
	v_permlane32_swap_b32_e32 v134, v135
	v_lshlrev_b32_e32 v132, 5, v154
	v_add_u32_e32 v179, s0, v132
	v_cmp_eq_u32_e32 vcc, 0, v146
	v_lshl_add_u32 v133, s23, 2, v179
	s_and_saveexec_b64 s[8:9], vcc
	s_cbranch_execz .LBB0_244
	s_waitcnt lgkmcnt(0)
	v_add_f32_e32 v134, v134, v135
	ds_write_b32 v133, v134
.LBB0_244:
	s_or_b64 exec, exec, s[8:9]
	v_mul_f32_e32 v134, v119, v119
	s_waitcnt lgkmcnt(0)
	v_mul_f32_e32 v135, v121, v121
	v_fmac_f32_e32 v134, v118, v118
	v_fmac_f32_e32 v135, v120, v120
	v_add_f32_e32 v134, v134, v135
	v_mul_f32_e32 v135, v115, v115
	v_fmac_f32_e32 v135, v114, v114
	v_add_f32_e32 v134, v134, v135
	v_mul_f32_e32 v135, v117, v117
	v_fmac_f32_e32 v135, v116, v116
	v_add_f32_e32 v134, v135, v134
	v_mov_b32_e32 v135, v134
	s_nop 1
	v_permlane16_swap_b32_e32 v134, v135
	s_waitcnt lgkmcnt(0)
	v_add_f32_e32 v134, v134, v135
	v_mov_b32_e32 v135, v134
	s_nop 1
	v_permlane32_swap_b32_e32 v134, v135
	s_and_saveexec_b64 s[8:9], vcc
	s_cbranch_execz .LBB0_246
	s_waitcnt lgkmcnt(0)
	v_add_f32_e32 v134, v134, v135
	ds_write_b32 v133, v134 offset:16
.LBB0_246:
	s_or_b64 exec, exec, s[8:9]
	v_mul_f32_e32 v133, v111, v111
	v_mul_f32_e32 v134, v113, v113
	v_fmac_f32_e32 v133, v110, v110
	v_fmac_f32_e32 v134, v112, v112
	v_add_f32_e32 v133, v133, v134
	v_mul_f32_e32 v134, v107, v107
	v_fmac_f32_e32 v134, v106, v106
	v_add_f32_e32 v133, v133, v134
	v_mul_f32_e32 v134, v109, v109
	v_fmac_f32_e32 v134, v108, v108
	v_add_f32_e32 v133, v134, v133
	v_mov_b32_e32 v134, v133
	s_nop 1
	v_permlane16_swap_b32_e32 v133, v134
	v_readlane_b32 s8, v255, 34
	s_waitcnt lgkmcnt(0)
	v_add_f32_e32 v134, v133, v134
	v_mov_b32_e32 v135, v134
	s_nop 1
	v_permlane32_swap_b32_e32 v134, v135
	v_add_u32_e32 v133, s8, v132
	s_and_saveexec_b64 s[8:9], vcc
	s_cbranch_execz .LBB0_248
	s_waitcnt lgkmcnt(0)
	v_add_f32_e32 v134, v134, v135
	ds_write_b32 v133, v134
.LBB0_248:
	s_or_b64 exec, exec, s[8:9]
	v_mul_f32_e32 v134, v103, v103
	s_waitcnt lgkmcnt(0)
	v_mul_f32_e32 v135, v105, v105
	v_fmac_f32_e32 v134, v102, v102
	v_fmac_f32_e32 v135, v104, v104
	v_add_f32_e32 v134, v134, v135
	v_mul_f32_e32 v135, v99, v99
	v_fmac_f32_e32 v135, v98, v98
	v_add_f32_e32 v134, v134, v135
	v_mul_f32_e32 v135, v101, v101
	v_fmac_f32_e32 v135, v100, v100
	v_add_f32_e32 v134, v135, v134
	v_mov_b32_e32 v135, v134
	s_nop 1
	v_permlane16_swap_b32_e32 v134, v135
	s_waitcnt lgkmcnt(0)
	v_add_f32_e32 v134, v134, v135
	v_mov_b32_e32 v135, v134
	s_nop 1
	v_permlane32_swap_b32_e32 v134, v135
	s_and_saveexec_b64 s[8:9], vcc
	s_cbranch_execz .LBB0_250
	s_waitcnt lgkmcnt(0)
	v_add_f32_e32 v134, v134, v135
	ds_write_b32 v133, v134 offset:16
.LBB0_250:
	s_or_b64 exec, exec, s[8:9]
	v_mul_f32_e32 v133, v95, v95
	v_mul_f32_e32 v134, v97, v97
	v_fmac_f32_e32 v133, v94, v94
	v_fmac_f32_e32 v134, v96, v96
	v_add_f32_e32 v133, v133, v134
	v_mul_f32_e32 v134, v91, v91
	v_fmac_f32_e32 v134, v90, v90
	v_add_f32_e32 v133, v133, v134
	v_mul_f32_e32 v134, v93, v93
	v_fmac_f32_e32 v134, v92, v92
	v_add_f32_e32 v133, v134, v133
	v_mov_b32_e32 v134, v133
	s_nop 1
	v_permlane16_swap_b32_e32 v133, v134
	v_readlane_b32 s8, v255, 36
	s_waitcnt lgkmcnt(0)
	v_add_f32_e32 v134, v133, v134
	v_mov_b32_e32 v135, v134
	s_nop 1
	v_permlane32_swap_b32_e32 v134, v135
	v_add_u32_e32 v133, s8, v132
	s_and_saveexec_b64 s[8:9], vcc
	s_cbranch_execz .LBB0_252
	s_waitcnt lgkmcnt(0)
	v_add_f32_e32 v134, v134, v135
	ds_write_b32 v133, v134
.LBB0_252:
	s_or_b64 exec, exec, s[8:9]
	v_mul_f32_e32 v134, v87, v87
	s_waitcnt lgkmcnt(0)
	v_mul_f32_e32 v135, v89, v89
	v_fmac_f32_e32 v134, v86, v86
	v_fmac_f32_e32 v135, v88, v88
	v_add_f32_e32 v134, v134, v135
	v_mul_f32_e32 v135, v83, v83
	v_fmac_f32_e32 v135, v82, v82
	v_add_f32_e32 v134, v134, v135
	v_mul_f32_e32 v135, v85, v85
	v_fmac_f32_e32 v135, v84, v84
	v_add_f32_e32 v134, v135, v134
	v_mov_b32_e32 v135, v134
	s_nop 1
	v_permlane16_swap_b32_e32 v134, v135
	s_waitcnt lgkmcnt(0)
	v_add_f32_e32 v134, v134, v135
	v_mov_b32_e32 v135, v134
	s_nop 1
	v_permlane32_swap_b32_e32 v134, v135
	s_and_saveexec_b64 s[8:9], vcc
	s_cbranch_execz .LBB0_254
	s_waitcnt lgkmcnt(0)
	v_add_f32_e32 v134, v134, v135
	ds_write_b32 v133, v134 offset:16
.LBB0_254:
	s_or_b64 exec, exec, s[8:9]
	v_mul_f32_e32 v133, v79, v79
	v_mul_f32_e32 v134, v81, v81
	v_fmac_f32_e32 v133, v78, v78
	v_fmac_f32_e32 v134, v80, v80
	v_add_f32_e32 v133, v133, v134
	v_mul_f32_e32 v134, v75, v75
	v_fmac_f32_e32 v134, v74, v74
	v_add_f32_e32 v133, v133, v134
	v_mul_f32_e32 v134, v77, v77
	v_fmac_f32_e32 v134, v76, v76
	v_add_f32_e32 v133, v134, v133
	v_mov_b32_e32 v134, v133
	s_nop 1
	v_permlane16_swap_b32_e32 v133, v134
	s_waitcnt lgkmcnt(0)
	v_add_f32_e32 v134, v133, v134
	v_mov_b32_e32 v135, v134
	s_nop 1
	v_permlane32_swap_b32_e32 v134, v135
	v_add_u32_e32 v133, s41, v132
	s_and_saveexec_b64 s[8:9], vcc
	s_cbranch_execz .LBB0_256
	s_waitcnt lgkmcnt(0)
	v_add_f32_e32 v134, v134, v135
	ds_write_b32 v133, v134
.LBB0_256:
	s_or_b64 exec, exec, s[8:9]
	v_mul_f32_e32 v134, v71, v71
	s_waitcnt lgkmcnt(0)
	v_mul_f32_e32 v135, v73, v73
	v_fmac_f32_e32 v134, v70, v70
	v_fmac_f32_e32 v135, v72, v72
	v_add_f32_e32 v134, v134, v135
	v_mul_f32_e32 v135, v67, v67
	v_fmac_f32_e32 v135, v66, v66
	v_add_f32_e32 v134, v134, v135
	v_mul_f32_e32 v135, v69, v69
	v_fmac_f32_e32 v135, v68, v68
	v_add_f32_e32 v134, v135, v134
	v_mov_b32_e32 v135, v134
	s_nop 1
	v_permlane16_swap_b32_e32 v134, v135
	s_waitcnt lgkmcnt(0)
	v_add_f32_e32 v134, v134, v135
	v_mov_b32_e32 v135, v134
	s_nop 1
	v_permlane32_swap_b32_e32 v134, v135
	s_and_saveexec_b64 s[8:9], vcc
	s_cbranch_execz .LBB0_258
	s_waitcnt lgkmcnt(0)
	v_add_f32_e32 v134, v134, v135
	ds_write_b32 v133, v134 offset:16
.LBB0_258:
	s_or_b64 exec, exec, s[8:9]
	v_mul_f32_e32 v133, v63, v63
	v_mul_f32_e32 v134, v65, v65
	v_fmac_f32_e32 v133, v62, v62
	v_fmac_f32_e32 v134, v64, v64
	v_add_f32_e32 v133, v133, v134
	v_mul_f32_e32 v134, v59, v59
	v_fmac_f32_e32 v134, v58, v58
	v_add_f32_e32 v133, v133, v134
	v_mul_f32_e32 v134, v61, v61
	v_fmac_f32_e32 v134, v60, v60
	v_add_f32_e32 v133, v134, v133
	v_mov_b32_e32 v134, v133
	s_nop 1
	v_permlane16_swap_b32_e32 v133, v134
	s_waitcnt lgkmcnt(0)
	v_add_f32_e32 v134, v133, v134
	v_mov_b32_e32 v135, v134
	s_nop 1
	v_permlane32_swap_b32_e32 v134, v135
	v_add_u32_e32 v133, s97, v132
	s_and_saveexec_b64 s[8:9], vcc
	s_cbranch_execz .LBB0_260
	s_waitcnt lgkmcnt(0)
	v_add_f32_e32 v134, v134, v135
	ds_write_b32 v133, v134
.LBB0_260:
	s_or_b64 exec, exec, s[8:9]
	v_mul_f32_e32 v134, v55, v55
	s_waitcnt lgkmcnt(0)
	v_mul_f32_e32 v135, v57, v57
	v_fmac_f32_e32 v134, v54, v54
	v_fmac_f32_e32 v135, v56, v56
	v_add_f32_e32 v134, v134, v135
	v_mul_f32_e32 v135, v51, v51
	v_fmac_f32_e32 v135, v50, v50
	v_add_f32_e32 v134, v134, v135
	v_mul_f32_e32 v135, v53, v53
	v_fmac_f32_e32 v135, v52, v52
	v_add_f32_e32 v134, v135, v134
	v_mov_b32_e32 v135, v134
	s_nop 1
	v_permlane16_swap_b32_e32 v134, v135
	s_waitcnt lgkmcnt(0)
	v_add_f32_e32 v134, v134, v135
	v_mov_b32_e32 v135, v134
	s_nop 1
	v_permlane32_swap_b32_e32 v134, v135
	s_and_saveexec_b64 s[8:9], vcc
	s_cbranch_execz .LBB0_262
	s_waitcnt lgkmcnt(0)
	v_add_f32_e32 v134, v134, v135
	ds_write_b32 v133, v134 offset:16
.LBB0_262:
	s_or_b64 exec, exec, s[8:9]
	v_mul_f32_e32 v133, v47, v47
	v_mul_f32_e32 v134, v49, v49
	v_fmac_f32_e32 v133, v46, v46
	v_fmac_f32_e32 v134, v48, v48
	v_add_f32_e32 v133, v133, v134
	v_mul_f32_e32 v134, v43, v43
	v_fmac_f32_e32 v134, v42, v42
	v_add_f32_e32 v133, v133, v134
	v_mul_f32_e32 v134, v45, v45
	v_fmac_f32_e32 v134, v44, v44
	v_add_f32_e32 v133, v134, v133
	v_mov_b32_e32 v134, v133
	s_nop 1
	v_permlane16_swap_b32_e32 v133, v134
	s_waitcnt lgkmcnt(0)
	v_add_f32_e32 v134, v133, v134
	v_mov_b32_e32 v135, v134
	s_nop 1
	v_permlane32_swap_b32_e32 v134, v135
	v_add_u32_e32 v133, s54, v132
	s_and_saveexec_b64 s[8:9], vcc
	s_cbranch_execz .LBB0_264
	s_waitcnt lgkmcnt(0)
	v_add_f32_e32 v134, v134, v135
	ds_write_b32 v133, v134
.LBB0_264:
	s_or_b64 exec, exec, s[8:9]
	v_mul_f32_e32 v134, v39, v39
	s_waitcnt lgkmcnt(0)
	v_mul_f32_e32 v135, v41, v41
	v_fmac_f32_e32 v134, v38, v38
	v_fmac_f32_e32 v135, v40, v40
	v_add_f32_e32 v134, v134, v135
	v_mul_f32_e32 v135, v35, v35
	v_fmac_f32_e32 v135, v34, v34
	v_add_f32_e32 v134, v134, v135
	v_mul_f32_e32 v135, v37, v37
	v_fmac_f32_e32 v135, v36, v36
	v_add_f32_e32 v134, v135, v134
	v_mov_b32_e32 v135, v134
	s_nop 1
	v_permlane16_swap_b32_e32 v134, v135
	s_waitcnt lgkmcnt(0)
	v_add_f32_e32 v134, v134, v135
	v_mov_b32_e32 v135, v134
	s_nop 1
	v_permlane32_swap_b32_e32 v134, v135
	s_and_saveexec_b64 s[8:9], vcc
	s_cbranch_execz .LBB0_266
	s_waitcnt lgkmcnt(0)
	v_add_f32_e32 v134, v134, v135
	ds_write_b32 v133, v134 offset:16
.LBB0_266:
	s_or_b64 exec, exec, s[8:9]
	v_mul_f32_e32 v133, v31, v31
	v_mul_f32_e32 v134, v33, v33
	v_fmac_f32_e32 v133, v30, v30
	v_fmac_f32_e32 v134, v32, v32
	v_add_f32_e32 v133, v133, v134
	v_mul_f32_e32 v134, v27, v27
	v_fmac_f32_e32 v134, v26, v26
	v_add_f32_e32 v133, v133, v134
	v_mul_f32_e32 v134, v29, v29
	v_fmac_f32_e32 v134, v28, v28
	v_add_f32_e32 v133, v134, v133
	v_mov_b32_e32 v134, v133
	s_nop 1
	v_permlane16_swap_b32_e32 v133, v134
	s_waitcnt lgkmcnt(0)
	v_add_f32_e32 v134, v133, v134
	v_mov_b32_e32 v135, v134
	s_nop 1
	v_permlane32_swap_b32_e32 v134, v135
	v_add_u32_e32 v133, s55, v132
	s_and_saveexec_b64 s[8:9], vcc
	s_cbranch_execz .LBB0_268
	s_waitcnt lgkmcnt(0)
	v_add_f32_e32 v134, v134, v135
	ds_write_b32 v133, v134
.LBB0_268:
	s_or_b64 exec, exec, s[8:9]
	v_mul_f32_e32 v134, v23, v23
	s_waitcnt lgkmcnt(0)
	v_mul_f32_e32 v135, v25, v25
	v_fmac_f32_e32 v134, v22, v22
	v_fmac_f32_e32 v135, v24, v24
	v_add_f32_e32 v134, v134, v135
	v_mul_f32_e32 v135, v19, v19
	v_fmac_f32_e32 v135, v18, v18
	v_add_f32_e32 v134, v134, v135
	v_mul_f32_e32 v135, v21, v21
	v_fmac_f32_e32 v135, v20, v20
	v_add_f32_e32 v134, v135, v134
	v_mov_b32_e32 v135, v134
	s_nop 1
	v_permlane16_swap_b32_e32 v134, v135
	s_waitcnt lgkmcnt(0)
	v_add_f32_e32 v134, v134, v135
	v_mov_b32_e32 v135, v134
	s_nop 1
	v_permlane32_swap_b32_e32 v134, v135
	s_and_saveexec_b64 s[8:9], vcc
	s_cbranch_execz .LBB0_270
	s_waitcnt lgkmcnt(0)
	v_add_f32_e32 v134, v134, v135
	ds_write_b32 v133, v134 offset:16
.LBB0_270:
	s_or_b64 exec, exec, s[8:9]
	v_mul_f32_e32 v133, v15, v15
	v_mul_f32_e32 v134, v17, v17
	v_fmac_f32_e32 v133, v14, v14
	v_fmac_f32_e32 v134, v16, v16
	v_add_f32_e32 v133, v133, v134
	v_mul_f32_e32 v134, v11, v11
	v_fmac_f32_e32 v134, v10, v10
	v_add_f32_e32 v133, v133, v134
	v_mul_f32_e32 v134, v13, v13
	v_fmac_f32_e32 v134, v12, v12
	v_add_f32_e32 v133, v134, v133
	v_mov_b32_e32 v134, v133
	s_nop 1
	v_permlane16_swap_b32_e32 v133, v134
	v_add_u32_e32 v132, s33, v132
	s_waitcnt lgkmcnt(0)
	v_add_f32_e32 v133, v133, v134
	v_mov_b32_e32 v134, v133
	s_nop 1
	v_permlane32_swap_b32_e32 v133, v134
	s_and_saveexec_b64 s[8:9], vcc
	s_cbranch_execz .LBB0_272
	s_waitcnt lgkmcnt(0)
	v_add_f32_e32 v133, v133, v134
	ds_write_b32 v132, v133
.LBB0_272:
	s_or_b64 exec, exec, s[8:9]
	v_mul_f32_e32 v133, v7, v7
	s_waitcnt lgkmcnt(0)
	v_mul_f32_e32 v134, v9, v9
	v_fmac_f32_e32 v133, v6, v6
	v_fmac_f32_e32 v134, v8, v8
	v_add_f32_e32 v133, v133, v134
	v_mul_f32_e32 v134, v3, v3
	v_fmac_f32_e32 v134, v2, v2
	v_add_f32_e32 v133, v133, v134
	v_mul_f32_e32 v134, v5, v5
	v_fmac_f32_e32 v134, v4, v4
	v_add_f32_e32 v133, v134, v133
	v_mov_b32_e32 v130, v133
	s_nop 1
	v_permlane16_swap_b32_e32 v133, v130
	s_waitcnt lgkmcnt(0)
	v_add_f32_e32 v130, v133, v130
	v_mov_b32_e32 v131, v130
	s_nop 1
	v_permlane32_swap_b32_e32 v130, v131
	s_and_saveexec_b64 s[8:9], vcc
	s_cbranch_execz .LBB0_274
	s_waitcnt lgkmcnt(0)
	v_add_f32_e32 v130, v130, v131
	ds_write_b32 v132, v130 offset:16

.LBB0_598:
	s_lshl_b32 s6, s80, 8
	s_add_i32 s3, s2, -16
	s_or_b32 s6, s6, s29
	s_ashr_i32 s8, s2, 31
	s_cmp_lt_i32 s2, 16
	v_mov_b32_e32 v164, v1
	v_mov_b32_e32 v165, v190
	s_cselect_b64 s[82:83], -1, 0
	v_mul_f32_e32 v166, v129, v129
	v_lshl_add_u32 v162, v165, 3, s6
	s_and_b64 s[6:7], s[82:83], exec
	s_cselect_b32 s7, s8, 0
	s_cselect_b32 s6, s2, s3
	s_cselect_b32 s8, s39, s41
	s_cselect_b32 s9, s38, s40
	s_lshl_b64 s[6:7], s[6:7], 21
	s_add_u32 s6, s9, s6
	v_add_u32_e32 v160, s28, v164
	s_addc_u32 s7, s8, s7
	v_ashrrev_i32_e32 v163, 31, v162
	v_ashrrev_i32_e32 v161, 31, v160
	v_add_u32_e32 v158, 16, v160
	v_lshl_add_u64 v[176:177], v[162:163], 2, s[6:7]
	v_lshlrev_b64 v[130:131], 13, v[160:161]
	v_ashrrev_i32_e32 v159, 31, v158
	v_add_u32_e32 v156, 32, v160
	v_lshl_add_u64 v[174:175], v[176:177], 0, v[130:131]
	v_lshlrev_b64 v[130:131], 13, v[158:159]
	v_ashrrev_i32_e32 v157, 31, v156
	v_add_u32_e32 v154, 48, v160
	v_lshl_add_u64 v[172:173], v[176:177], 0, v[130:131]
	v_lshlrev_b64 v[130:131], 13, v[156:157]
	v_ashrrev_i32_e32 v155, 31, v154
	v_lshl_add_u64 v[170:171], v[176:177], 0, v[130:131]
	v_lshlrev_b64 v[130:131], 13, v[154:155]
	global_load_dwordx4 v[142:145], v[174:175], off nt
	global_load_dwordx4 v[138:141], v[172:173], off nt
	v_lshl_add_u64 v[168:169], v[176:177], 0, v[130:131]
	global_load_dwordx4 v[134:137], v[170:171], off nt
	global_load_dwordx4 v[130:133], v[168:169], off nt
	v_and_b32_e32 v157, 64, v195
	v_xor_b32_e32 v155, 16, v195
	v_add_u32_e32 v159, 64, v157
	v_cmp_lt_i32_e32 vcc, v155, v159
	v_mul_f32_e32 v161, v125, v125
	v_fmac_f32_e32 v161, v124, v124
	v_cndmask_b32_e32 v155, v195, v155, vcc
	v_lshlrev_b32_e32 v157, 2, v155
	v_mul_f32_e32 v155, v123, v123
	v_fmac_f32_e32 v155, v122, v122
	v_add_f32_e32 v155, v155, v161
	v_mul_f32_e32 v161, v127, v127
	v_fmac_f32_e32 v161, v126, v126
	v_fmac_f32_e32 v166, v128, v128
	v_add_f32_e32 v161, v161, v166
	v_add_f32_e32 v155, v155, v161
	v_mul_f32_e32 v161, v87, v87
	v_mul_f32_e32 v166, v89, v89
	v_fmac_f32_e32 v161, v86, v86
	v_fmac_f32_e32 v166, v88, v88
	v_add_f32_e32 v161, v161, v166
	v_add_f32_e32 v155, v155, v161
	v_mul_f32_e32 v161, v83, v83
	v_mul_f32_e32 v166, v85, v85
	v_fmac_f32_e32 v161, v82, v82
	v_fmac_f32_e32 v166, v84, v84
	v_add_f32_e32 v161, v161, v166
	v_add_f32_e32 v155, v155, v161
	v_mov_b32_e32 v166, v155
	s_nop 1
	v_permlane16_swap_b32_e32 v155, v166
	v_xor_b32_e32 v161, 32, v195
	v_cmp_lt_i32_e32 vcc, v161, v159
	v_cmp_eq_u32_e64 s[6:7], 0, v165
	s_waitcnt lgkmcnt(0)
	v_add_f32_e32 v155, v155, v166
	v_cndmask_b32_e32 v159, v195, v161, vcc
	v_lshlrev_b32_e32 v161, 2, v159
	v_mov_b32_e32 v166, v155
	s_nop 1
	v_permlane32_swap_b32_e32 v155, v166
	v_lshl_add_u32 v159, v164, 4, s55
	s_and_saveexec_b64 s[8:9], s[6:7]
	s_cbranch_execz .LBB0_600
	s_waitcnt lgkmcnt(0)
	v_add_f32_e32 v155, v155, v166
	ds_write_b32 v159, v155
.LBB0_600:
	s_or_b64 exec, exec, s[8:9]
	v_mul_f32_e32 v155, v115, v115
	s_waitcnt lgkmcnt(0)
	v_mul_f32_e32 v166, v117, v117
	v_fmac_f32_e32 v155, v114, v114
	v_fmac_f32_e32 v166, v116, v116
	v_add_f32_e32 v155, v155, v166
	v_mul_f32_e32 v166, v119, v119
	v_mul_f32_e32 v167, v121, v121
	v_fmac_f32_e32 v166, v118, v118
	v_fmac_f32_e32 v167, v120, v120
	v_add_f32_e32 v166, v166, v167
	v_add_f32_e32 v155, v155, v166
	v_mul_f32_e32 v166, v91, v91
	v_mul_f32_e32 v167, v93, v93
	v_fmac_f32_e32 v166, v90, v90
	v_fmac_f32_e32 v167, v92, v92
	v_add_f32_e32 v166, v166, v167
	v_add_f32_e32 v155, v155, v166
	v_mul_f32_e32 v166, v107, v107
	v_mul_f32_e32 v167, v109, v109
	v_fmac_f32_e32 v166, v106, v106
	v_fmac_f32_e32 v167, v108, v108
	v_add_f32_e32 v166, v166, v167
	v_add_f32_e32 v155, v155, v166
	v_mov_b32_e32 v166, v155
	s_nop 1
	v_permlane16_swap_b32_e32 v155, v166
	s_waitcnt lgkmcnt(0)
	v_add_f32_e32 v155, v155, v166
	v_mov_b32_e32 v166, v155
	s_nop 1
	v_permlane32_swap_b32_e32 v155, v166
	s_and_saveexec_b64 s[8:9], s[6:7]
	s_cbranch_execz .LBB0_602
	s_waitcnt lgkmcnt(0)
	v_add_f32_e32 v155, v155, v166
	ds_write_b32 v159, v155 offset:256
.LBB0_602:
	s_or_b64 exec, exec, s[8:9]
	v_mul_f32_e32 v155, v35, v35
	s_waitcnt lgkmcnt(0)
	v_mul_f32_e32 v166, v37, v37
	v_fmac_f32_e32 v155, v34, v34
	v_fmac_f32_e32 v166, v36, v36
	v_add_f32_e32 v155, v155, v166
	v_mul_f32_e32 v166, v31, v31
	v_mul_f32_e32 v167, v33, v33
	v_fmac_f32_e32 v166, v30, v30
	v_fmac_f32_e32 v167, v32, v32
	v_add_f32_e32 v166, v166, v167
	v_add_f32_e32 v155, v155, v166
	v_mul_f32_e32 v166, v103, v103
	v_mul_f32_e32 v167, v105, v105
	v_fmac_f32_e32 v166, v102, v102
	v_fmac_f32_e32 v167, v104, v104
	v_add_f32_e32 v166, v166, v167
	v_add_f32_e32 v155, v155, v166
	v_mul_f32_e32 v166, v99, v99
	v_mul_f32_e32 v167, v101, v101
	v_fmac_f32_e32 v166, v98, v98
	v_fmac_f32_e32 v167, v100, v100
	v_add_f32_e32 v166, v166, v167
	v_add_f32_e32 v155, v155, v166
	v_mov_b32_e32 v166, v155
	s_nop 1
	v_permlane16_swap_b32_e32 v155, v166
	s_waitcnt lgkmcnt(0)
	v_add_f32_e32 v155, v155, v166
	v_mov_b32_e32 v166, v155
	s_nop 1
	v_permlane32_swap_b32_e32 v155, v166
	s_and_saveexec_b64 s[8:9], s[6:7]
	s_cbranch_execz .LBB0_604
	s_waitcnt lgkmcnt(0)
	v_add_f32_e32 v155, v155, v166
	ds_write_b32 v159, v155 offset:512
.LBB0_604:
	s_or_b64 exec, exec, s[8:9]
	v_mul_f32_e32 v155, v23, v23
	s_waitcnt lgkmcnt(0)
	v_mul_f32_e32 v166, v25, v25
	v_fmac_f32_e32 v155, v22, v22
	v_fmac_f32_e32 v166, v24, v24
	v_add_f32_e32 v155, v155, v166
	v_mul_f32_e32 v166, v19, v19
	v_mul_f32_e32 v167, v21, v21
	v_fmac_f32_e32 v166, v18, v18
	v_fmac_f32_e32 v167, v20, v20
	v_add_f32_e32 v166, v166, v167
	v_add_f32_e32 v155, v155, v166
	v_mul_f32_e32 v166, v79, v79
	v_mul_f32_e32 v167, v81, v81
	v_fmac_f32_e32 v166, v78, v78
	v_fmac_f32_e32 v167, v80, v80
	v_add_f32_e32 v166, v166, v167
	v_add_f32_e32 v155, v155, v166
	v_mul_f32_e32 v166, v75, v75
	v_mul_f32_e32 v167, v77, v77
	v_fmac_f32_e32 v166, v74, v74
	v_fmac_f32_e32 v167, v76, v76
	v_add_f32_e32 v166, v166, v167
	v_add_f32_e32 v155, v155, v166
	v_mov_b32_e32 v166, v155
	s_nop 1
	v_permlane16_swap_b32_e32 v155, v166
	s_waitcnt lgkmcnt(0)
	v_add_f32_e32 v155, v155, v166
	v_mov_b32_e32 v166, v155
	s_nop 1
	v_permlane32_swap_b32_e32 v155, v166
	s_and_saveexec_b64 s[8:9], s[6:7]
	s_cbranch_execz .LBB0_606
	s_waitcnt lgkmcnt(0)
	v_add_f32_e32 v155, v155, v166
	ds_write_b32 v159, v155 offset:768
.LBB0_606:
	s_or_b64 exec, exec, s[8:9]
	v_mul_f32_e32 v155, v43, v43
	s_waitcnt lgkmcnt(0)
	v_mul_f32_e32 v166, v45, v45
	v_fmac_f32_e32 v155, v42, v42
	v_fmac_f32_e32 v166, v44, v44
	v_add_f32_e32 v155, v155, v166
	v_mul_f32_e32 v166, v39, v39
	v_mul_f32_e32 v167, v41, v41
	v_fmac_f32_e32 v166, v38, v38
	v_fmac_f32_e32 v167, v40, v40
	v_add_f32_e32 v166, v166, v167
	v_add_f32_e32 v155, v155, v166
	v_mul_f32_e32 v166, v55, v55
	v_mul_f32_e32 v167, v57, v57
	v_fmac_f32_e32 v166, v54, v54
	v_fmac_f32_e32 v167, v56, v56
	v_add_f32_e32 v166, v166, v167
	v_add_f32_e32 v155, v155, v166
	v_mul_f32_e32 v166, v51, v51
	v_mul_f32_e32 v167, v53, v53
	v_fmac_f32_e32 v166, v50, v50
	v_fmac_f32_e32 v167, v52, v52
	v_add_f32_e32 v166, v166, v167
	v_add_f32_e32 v155, v155, v166
	v_mov_b32_e32 v166, v155
	s_nop 1
	v_permlane16_swap_b32_e32 v155, v166
	s_waitcnt lgkmcnt(0)
	v_add_f32_e32 v155, v155, v166
	v_mov_b32_e32 v166, v155
	s_nop 1
	v_permlane32_swap_b32_e32 v155, v166
	s_and_saveexec_b64 s[8:9], s[6:7]
	s_cbranch_execz .LBB0_608
	s_waitcnt lgkmcnt(0)
	v_add_f32_e32 v155, v155, v166
	ds_write_b32 v159, v155 offset:2048
.LBB0_608:
	s_or_b64 exec, exec, s[8:9]
	v_mul_f32_e32 v155, v63, v63
	s_waitcnt lgkmcnt(0)
	v_mul_f32_e32 v166, v65, v65
	v_fmac_f32_e32 v155, v62, v62
	v_fmac_f32_e32 v166, v64, v64
	v_add_f32_e32 v155, v155, v166
	v_mul_f32_e32 v166, v59, v59
	v_mul_f32_e32 v167, v61, v61
	v_fmac_f32_e32 v166, v58, v58
	v_fmac_f32_e32 v167, v60, v60
	v_add_f32_e32 v166, v166, v167
	v_add_f32_e32 v155, v155, v166
	v_mul_f32_e32 v166, v47, v47
	v_mul_f32_e32 v167, v49, v49
	v_fmac_f32_e32 v166, v46, v46
	v_fmac_f32_e32 v167, v48, v48
	v_add_f32_e32 v166, v166, v167
	v_add_f32_e32 v155, v155, v166
	v_mul_f32_e32 v166, v27, v27
	v_mul_f32_e32 v167, v29, v29
	v_fmac_f32_e32 v166, v26, v26
	v_fmac_f32_e32 v167, v28, v28
	v_add_f32_e32 v166, v166, v167
	v_add_f32_e32 v155, v155, v166
	v_mov_b32_e32 v166, v155
	s_nop 1
	v_permlane16_swap_b32_e32 v155, v166
	s_waitcnt lgkmcnt(0)
	v_add_f32_e32 v155, v155, v166
	v_mov_b32_e32 v166, v155
	s_nop 1
	v_permlane32_swap_b32_e32 v155, v166
	s_and_saveexec_b64 s[8:9], s[6:7]
	s_cbranch_execz .LBB0_610
	s_waitcnt lgkmcnt(0)
	v_add_f32_e32 v155, v155, v166
	ds_write_b32 v159, v155 offset:2304
.LBB0_610:
	s_or_b64 exec, exec, s[8:9]
	v_mul_f32_e32 v155, v71, v71
	s_waitcnt lgkmcnt(0)
	v_mul_f32_e32 v166, v73, v73
	v_fmac_f32_e32 v155, v70, v70
	v_fmac_f32_e32 v166, v72, v72
	v_add_f32_e32 v155, v155, v166
	v_mul_f32_e32 v166, v67, v67
	v_mul_f32_e32 v167, v69, v69
	v_fmac_f32_e32 v166, v66, v66
	v_fmac_f32_e32 v167, v68, v68
	v_add_f32_e32 v166, v166, v167
	v_add_f32_e32 v155, v155, v166
	v_mul_f32_e32 v166, v15, v15
	v_mul_f32_e32 v167, v17, v17
	v_fmac_f32_e32 v166, v14, v14
	v_fmac_f32_e32 v167, v16, v16
	v_add_f32_e32 v166, v166, v167
	v_add_f32_e32 v155, v155, v166
	v_mul_f32_e32 v166, v11, v11
	v_mul_f32_e32 v167, v13, v13
	v_fmac_f32_e32 v166, v10, v10
	v_fmac_f32_e32 v167, v12, v12
	v_add_f32_e32 v166, v166, v167
	v_add_f32_e32 v155, v155, v166
	v_mov_b32_e32 v166, v155
	s_nop 1
	v_permlane16_swap_b32_e32 v155, v166
	s_waitcnt lgkmcnt(0)
	v_add_f32_e32 v155, v155, v166
	v_mov_b32_e32 v166, v155
	s_nop 1
	v_permlane32_swap_b32_e32 v155, v166
	s_and_saveexec_b64 s[8:9], s[6:7]
	s_cbranch_execz .LBB0_612
	s_waitcnt lgkmcnt(0)
	v_add_f32_e32 v155, v155, v166
	ds_write_b32 v159, v155 offset:2560
.LBB0_612:
	s_or_b64 exec, exec, s[8:9]
	v_mul_f32_e32 v155, v95, v95
	s_waitcnt lgkmcnt(0)
	v_mul_f32_e32 v166, v97, v97
	v_fmac_f32_e32 v155, v94, v94
	v_fmac_f32_e32 v166, v96, v96
	v_add_f32_e32 v155, v155, v166
	v_mul_f32_e32 v166, v111, v111
	v_mul_f32_e32 v167, v113, v113
	v_fmac_f32_e32 v166, v110, v110
	v_fmac_f32_e32 v167, v112, v112
	v_add_f32_e32 v166, v166, v167
	v_add_f32_e32 v155, v155, v166
	v_mul_f32_e32 v166, v7, v7
	v_mul_f32_e32 v167, v9, v9
	v_fmac_f32_e32 v166, v6, v6
	v_fmac_f32_e32 v167, v8, v8
	v_add_f32_e32 v166, v166, v167
	v_add_f32_e32 v155, v155, v166
	v_mul_f32_e32 v166, v3, v3
	v_mul_f32_e32 v167, v5, v5
	v_fmac_f32_e32 v166, v2, v2
	v_fmac_f32_e32 v167, v4, v4
	v_add_f32_e32 v166, v166, v167
	v_add_f32_e32 v155, v155, v166
	v_mov_b32_e32 v166, v155
	s_nop 1
	v_permlane16_swap_b32_e32 v155, v166
	s_waitcnt lgkmcnt(0)
	v_add_f32_e32 v155, v155, v166
	v_mov_b32_e32 v166, v155
	s_nop 1
	v_permlane32_swap_b32_e32 v155, v166
	s_and_saveexec_b64 s[8:9], s[6:7]
	s_cbranch_execz .LBB0_614
	s_waitcnt lgkmcnt(0)
	v_add_f32_e32 v155, v155, v166
	ds_write_b32 v159, v155 offset:2816

.LBB0_636:
	s_or_b64 exec, exec, s[84:85]
	s_lshr_b32 s3, s3, 2
	s_add_i32 s3, s3, 1
	s_and_b64 s[20:21], s[82:83], exec
	s_cselect_b32 s3, 0, s3
	s_mul_i32 s20, s3, 0x6000
	v_readlane_b32 s82, v255, 14
	s_mul_hi_u32 s21, s3, 0x6000
	v_readlane_b32 s83, v255, 15
	s_add_u32 s20, s82, s20
	s_addc_u32 s21, s83, s21
	s_waitcnt lgkmcnt(0)
	v_lshlrev_b64 v[166:167], 2, v[162:163]
	v_lshl_add_u64 v[186:187], s[20:21], 0, v[166:167]
	s_mov_b64 s[20:21], 0x4000
	v_lshl_add_u64 v[178:179], v[186:187], 0, s[20:21]
	s_movk_i32 s20, 0x4000
	s_waitcnt lgkmcnt(0)
	s_barrier
	v_lshl_add_u64 v[180:181], s[42:43], 0, v[166:167]
	v_add_co_u32_e32 v186, vcc, s20, v186
	global_load_dwordx4 v[202:205], v[180:181], off offset:16
	global_load_dwordx4 v[182:185], v[180:181], off
	v_addc_co_u32_e32 v187, vcc, 0, v187, vcc
	global_load_dwordx4 v[206:209], v[186:187], off
	global_load_dwordx4 v[210:213], v[178:179], off offset:16
	v_lshl_add_u32 v155, v160, 2, 0
	v_add_u32_e32 v155, 0x21200, v155
	s_waitcnt vmcnt(0)
	v_pk_mul_f32 v[188:189], v[182:183], v[206:207]
	ds_read2_b32 v[206:207], v155 offset1:16
	v_pk_mul_f32 v[186:187], v[184:185], v[208:209]
	v_pk_mul_f32 v[182:183], v[204:205], v[212:213]
	v_pk_mul_f32 v[184:185], v[202:203], v[210:211]
	global_load_dwordx4 v[202:205], v[174:175], off offset:16 nt
	s_waitcnt lgkmcnt(0)
	v_pk_mul_f32 v[122:123], v[122:123], v[206:207] op_sel_hi:[1,0]
	v_pk_mul_f32 v[124:125], v[124:125], v[206:207] op_sel_hi:[1,0]
	v_pk_fma_f32 v[122:123], v[188:189], v[122:123], v[142:143]
	v_pk_fma_f32 v[124:125], v[186:187], v[124:125], v[144:145]
	global_load_dwordx4 v[142:145], v[172:173], off offset:16 nt
	v_pk_mul_f32 v[126:127], v[126:127], v[206:207] op_sel_hi:[1,0]
	v_pk_mul_f32 v[128:129], v[128:129], v[206:207] op_sel_hi:[1,0]
	s_waitcnt vmcnt(1)
	v_pk_fma_f32 v[126:127], v[184:185], v[126:127], v[202:203]
	v_mov_b32_e32 v202, v207
	v_pk_mul_f32 v[114:115], v[114:115], v[202:203] op_sel_hi:[1,0]
	v_pk_mul_f32 v[116:117], v[116:117], v[202:203] op_sel_hi:[1,0]
	v_pk_mul_f32 v[120:121], v[120:121], v[202:203] op_sel_hi:[1,0]
	v_pk_mul_f32 v[118:119], v[118:119], v[202:203] op_sel_hi:[1,0]
	v_pk_fma_f32 v[128:129], v[182:183], v[128:129], v[204:205]
	v_pk_fma_f32 v[116:117], v[186:187], v[116:117], v[140:141]
	v_pk_fma_f32 v[114:115], v[188:189], v[114:115], v[138:139]
	s_waitcnt vmcnt(0)
	v_pk_fma_f32 v[118:119], v[184:185], v[118:119], v[142:143]
	v_pk_fma_f32 v[120:121], v[182:183], v[120:121], v[144:145]
	s_nop 0
	ds_read2_b32 v[142:143], v155 offset0:32 offset1:48
	global_load_dwordx4 v[138:141], v[170:171], off offset:16 nt
	s_waitcnt lgkmcnt(0)
	v_pk_mul_f32 v[34:35], v[34:35], v[142:143] op_sel_hi:[1,0]
	v_pk_mul_f32 v[36:37], v[36:37], v[142:143] op_sel_hi:[1,0]
	v_pk_fma_f32 v[34:35], v[188:189], v[34:35], v[134:135]
	v_pk_fma_f32 v[36:37], v[186:187], v[36:37], v[136:137]
	global_load_dwordx4 v[134:137], v[168:169], off offset:16 nt
	v_pk_mul_f32 v[30:31], v[30:31], v[142:143] op_sel_hi:[1,0]
	v_pk_mul_f32 v[32:33], v[32:33], v[142:143] op_sel_hi:[1,0]
	s_waitcnt vmcnt(1)
	v_pk_fma_f32 v[30:31], v[184:185], v[30:31], v[138:139]
	v_pk_fma_f32 v[32:33], v[182:183], v[32:33], v[140:141]
	v_mov_b32_e32 v138, v143
	v_add_u32_e32 v140, 0x80, v160
	v_pk_mul_f32 v[22:23], v[22:23], v[138:139] op_sel_hi:[1,0]
	v_pk_mul_f32 v[24:25], v[24:25], v[138:139] op_sel_hi:[1,0]
	v_pk_mul_f32 v[18:19], v[18:19], v[138:139] op_sel_hi:[1,0]
	v_pk_mul_f32 v[20:21], v[20:21], v[138:139] op_sel_hi:[1,0]
	v_ashrrev_i32_e32 v141, 31, v140
	v_pk_fma_f32 v[24:25], v[186:187], v[24:25], v[132:133]
	v_pk_fma_f32 v[22:23], v[188:189], v[22:23], v[130:131]
	s_waitcnt vmcnt(0)
	v_pk_fma_f32 v[20:21], v[182:183], v[20:21], v[136:137]
	v_pk_fma_f32 v[18:19], v[184:185], v[18:19], v[134:135]
	v_lshlrev_b64 v[130:131], 13, v[140:141]
	v_lshl_add_u64 v[130:131], v[176:177], 0, v[130:131]
	global_load_dwordx4 v[132:135], v[130:131], off offset:16 nt
	global_load_dwordx4 v[136:139], v[130:131], off nt
	ds_read2_b32 v[206:207], v155 offset0:128 offset1:144
	s_waitcnt lgkmcnt(0)
	v_pk_mul_f32 v[44:45], v[44:45], v[206:207] op_sel_hi:[1,0]
	v_pk_mul_f32 v[38:39], v[38:39], v[206:207] op_sel_hi:[1,0]
	v_pk_mul_f32 v[40:41], v[40:41], v[206:207] op_sel_hi:[1,0]
	v_pk_mul_f32 v[42:43], v[42:43], v[206:207] op_sel_hi:[1,0]
	s_waitcnt vmcnt(1)
	v_pk_fma_f32 v[38:39], v[184:185], v[38:39], v[132:133]
	s_waitcnt vmcnt(0)
	v_pk_fma_f32 v[44:45], v[186:187], v[44:45], v[138:139]
	v_add_u32_e32 v138, 0x90, v160
	v_ashrrev_i32_e32 v139, 31, v138
	v_lshlrev_b64 v[132:133], 13, v[138:139]
	v_pk_fma_f32 v[40:41], v[182:183], v[40:41], v[134:135]
	v_lshl_add_u64 v[134:135], v[176:177], 0, v[132:133]
	global_load_dwordx4 v[142:145], v[134:135], off offset:16 nt
	global_load_dwordx4 v[202:205], v[134:135], off nt
	v_mov_b32_e32 v132, v207
	v_pk_mul_f32 v[58:59], v[58:59], v[132:133] op_sel_hi:[1,0]
	v_pk_mul_f32 v[62:63], v[62:63], v[132:133] op_sel_hi:[1,0]
	v_pk_mul_f32 v[64:65], v[64:65], v[132:133] op_sel_hi:[1,0]
	v_pk_mul_f32 v[60:61], v[60:61], v[132:133] op_sel_hi:[1,0]
	v_pk_fma_f32 v[42:43], v[188:189], v[42:43], v[136:137]
	s_waitcnt vmcnt(1)
	v_pk_fma_f32 v[58:59], v[184:185], v[58:59], v[142:143]
	v_add_u32_e32 v142, 0xa0, v160
	v_ashrrev_i32_e32 v143, 31, v142
	s_waitcnt vmcnt(0)
	v_pk_fma_f32 v[64:65], v[186:187], v[64:65], v[204:205]
	v_pk_fma_f32 v[62:63], v[188:189], v[62:63], v[202:203]
	v_pk_fma_f32 v[60:61], v[182:183], v[60:61], v[144:145]
	v_lshlrev_b64 v[132:133], 13, v[142:143]
	v_lshl_add_u64 v[132:133], v[176:177], 0, v[132:133]
	global_load_dwordx4 v[202:205], v[132:133], off offset:16 nt
	global_load_dwordx4 v[206:209], v[132:133], off nt
	ds_read2_b32 v[210:211], v155 offset0:160 offset1:176
	v_add_u32_e32 v144, 0xb0, v160
	v_ashrrev_i32_e32 v145, 31, v144
	v_lshlrev_b64 v[136:137], 13, v[144:145]
	v_lshl_add_u64 v[136:137], v[176:177], 0, v[136:137]
	s_waitcnt lgkmcnt(0)
	v_pk_mul_f32 v[70:71], v[70:71], v[210:211] op_sel_hi:[1,0]
	v_pk_mul_f32 v[72:73], v[72:73], v[210:211] op_sel_hi:[1,0]
	v_pk_mul_f32 v[66:67], v[66:67], v[210:211] op_sel_hi:[1,0]
	v_pk_mul_f32 v[68:69], v[68:69], v[210:211] op_sel_hi:[1,0]
	v_mov_b32_e32 v176, v211
	v_pk_mul_f32 v[94:95], v[94:95], v[176:177] op_sel_hi:[1,0]
	v_pk_mul_f32 v[96:97], v[96:97], v[176:177] op_sel_hi:[1,0]
	v_pk_mul_f32 v[110:111], v[110:111], v[176:177] op_sel_hi:[1,0]
	v_pk_mul_f32 v[112:113], v[112:113], v[176:177] op_sel_hi:[1,0]
	s_waitcnt vmcnt(1)
	v_pk_fma_f32 v[68:69], v[182:183], v[68:69], v[204:205]
	s_waitcnt vmcnt(0)
	v_pk_fma_f32 v[72:73], v[186:187], v[72:73], v[208:209]
	v_pk_fma_f32 v[70:71], v[188:189], v[70:71], v[206:207]
	v_pk_fma_f32 v[66:67], v[184:185], v[66:67], v[202:203]
	global_load_dwordx4 v[202:205], v[136:137], off offset:16 nt
	global_load_dwordx4 v[206:209], v[136:137], off nt
	s_waitcnt vmcnt(1)
	v_pk_fma_f32 v[112:113], v[182:183], v[112:113], v[204:205]
	s_waitcnt vmcnt(0)
	v_pk_fma_f32 v[96:97], v[186:187], v[96:97], v[208:209]
	v_pk_fma_f32 v[94:95], v[188:189], v[94:95], v[206:207]
	v_pk_fma_f32 v[110:111], v[184:185], v[110:111], v[202:203]
	s_nop 0
	global_load_dwordx4 v[184:187], v[180:181], off offset:528
	global_load_dwordx4 v[202:205], v[180:181], off offset:512
	global_load_dwordx4 v[206:209], v[178:179], off offset:528
	s_nop 0
	global_load_dwordx4 v[176:179], v[178:179], off offset:512
	s_waitcnt vmcnt(0)
	v_pk_mul_f32 v[180:181], v[204:205], v[178:179]
	v_pk_mul_f32 v[182:183], v[202:203], v[176:177]
	v_pk_mul_f32 v[176:177], v[186:187], v[208:209]
	v_pk_mul_f32 v[178:179], v[184:185], v[206:207]
	global_load_dwordx4 v[184:187], v[174:175], off offset:528 nt
	global_load_dwordx4 v[202:205], v[174:175], off offset:512 nt
	ds_read2_b32 v[188:189], v155 offset1:16
	s_waitcnt lgkmcnt(0)
	v_pk_mul_f32 v[84:85], v[84:85], v[188:189] op_sel_hi:[1,0]
	v_pk_mul_f32 v[82:83], v[82:83], v[188:189] op_sel_hi:[1,0]
	v_pk_mul_f32 v[88:89], v[88:89], v[188:189] op_sel_hi:[1,0]
	v_pk_mul_f32 v[86:87], v[86:87], v[188:189] op_sel_hi:[1,0]
	v_mov_b32_e32 v188, v189
	v_pk_mul_f32 v[92:93], v[92:93], v[188:189] op_sel_hi:[1,0]
	v_pk_mul_f32 v[90:91], v[90:91], v[188:189] op_sel_hi:[1,0]
	v_pk_mul_f32 v[108:109], v[108:109], v[188:189] op_sel_hi:[1,0]
	v_pk_mul_f32 v[106:107], v[106:107], v[188:189] op_sel_hi:[1,0]
	s_waitcnt vmcnt(1)
	v_pk_fma_f32 v[82:83], v[178:179], v[82:83], v[184:185]
	v_pk_fma_f32 v[84:85], v[176:177], v[84:85], v[186:187]
	global_load_dwordx4 v[184:187], v[172:173], off offset:528 nt
	s_nop 0
	global_load_dwordx4 v[172:175], v[172:173], off offset:512 nt
	s_waitcnt vmcnt(2)
	v_pk_fma_f32 v[86:87], v[182:183], v[86:87], v[202:203]
	v_pk_fma_f32 v[88:89], v[180:181], v[88:89], v[204:205]
	s_waitcnt vmcnt(1)
	v_pk_fma_f32 v[106:107], v[178:179], v[106:107], v[184:185]
	s_waitcnt vmcnt(0)
	v_pk_fma_f32 v[90:91], v[182:183], v[90:91], v[172:173]
	v_pk_fma_f32 v[92:93], v[180:181], v[92:93], v[174:175]
	v_pk_fma_f32 v[108:109], v[176:177], v[108:109], v[186:187]
	s_nop 0
	global_load_dwordx4 v[172:175], v[170:171], off offset:528 nt
	global_load_dwordx4 v[184:187], v[170:171], off offset:512 nt
	ds_read2_b32 v[188:189], v155 offset0:32 offset1:48
	s_waitcnt lgkmcnt(0)
	v_pk_mul_f32 v[102:103], v[102:103], v[188:189] op_sel_hi:[1,0]
	v_pk_mul_f32 v[104:105], v[104:105], v[188:189] op_sel_hi:[1,0]
	v_pk_mul_f32 v[98:99], v[98:99], v[188:189] op_sel_hi:[1,0]
	v_pk_mul_f32 v[100:101], v[100:101], v[188:189] op_sel_hi:[1,0]
	s_waitcnt vmcnt(1)
	v_pk_fma_f32 v[98:99], v[178:179], v[98:99], v[172:173]
	s_waitcnt vmcnt(0)
	v_pk_fma_f32 v[104:105], v[180:181], v[104:105], v[186:187]
	v_pk_fma_f32 v[102:103], v[182:183], v[102:103], v[184:185]
	global_load_dwordx4 v[170:173], v[168:169], off offset:528 nt
	global_load_dwordx4 v[184:187], v[168:169], off offset:512 nt
	v_mov_b32_e32 v168, v189
	v_pk_mul_f32 v[78:79], v[78:79], v[168:169] op_sel_hi:[1,0]
	v_pk_mul_f32 v[80:81], v[80:81], v[168:169] op_sel_hi:[1,0]
	v_pk_mul_f32 v[74:75], v[74:75], v[168:169] op_sel_hi:[1,0]
	v_pk_mul_f32 v[76:77], v[76:77], v[168:169] op_sel_hi:[1,0]
	v_pk_fma_f32 v[100:101], v[176:177], v[100:101], v[174:175]
	s_waitcnt vmcnt(1)
	v_pk_fma_f32 v[76:77], v[176:177], v[76:77], v[172:173]
	s_waitcnt vmcnt(0)
	v_pk_fma_f32 v[80:81], v[180:181], v[80:81], v[186:187]
	v_pk_fma_f32 v[78:79], v[182:183], v[78:79], v[184:185]
	v_pk_fma_f32 v[74:75], v[178:179], v[74:75], v[170:171]
	s_nop 0
	global_load_dwordx4 v[168:171], v[130:131], off offset:528 nt
	global_load_dwordx4 v[172:175], v[130:131], off offset:512 nt
	ds_read2_b32 v[130:131], v155 offset0:128 offset1:144
	s_waitcnt lgkmcnt(0)
	v_pk_mul_f32 v[54:55], v[54:55], v[130:131] op_sel_hi:[1,0]
	v_pk_mul_f32 v[56:57], v[56:57], v[130:131] op_sel_hi:[1,0]
	v_pk_mul_f32 v[50:51], v[50:51], v[130:131] op_sel_hi:[1,0]
	v_pk_mul_f32 v[52:53], v[52:53], v[130:131] op_sel_hi:[1,0]
	v_mov_b32_e32 v130, v131
	v_pk_mul_f32 v[46:47], v[46:47], v[130:131] op_sel_hi:[1,0]
	v_pk_mul_f32 v[48:49], v[48:49], v[130:131] op_sel_hi:[1,0]
	v_pk_mul_f32 v[26:27], v[26:27], v[130:131] op_sel_hi:[1,0]
	v_pk_mul_f32 v[28:29], v[28:29], v[130:131] op_sel_hi:[1,0]
	s_waitcnt vmcnt(1)
	v_pk_fma_f32 v[52:53], v[176:177], v[52:53], v[170:171]
	s_waitcnt vmcnt(0)
	v_pk_fma_f32 v[56:57], v[180:181], v[56:57], v[174:175]
	v_pk_fma_f32 v[54:55], v[182:183], v[54:55], v[172:173]
	v_pk_fma_f32 v[50:51], v[178:179], v[50:51], v[168:169]
	global_load_dwordx4 v[168:171], v[134:135], off offset:528 nt
	global_load_dwordx4 v[172:175], v[134:135], off offset:512 nt
	s_waitcnt vmcnt(1)
	v_pk_fma_f32 v[28:29], v[176:177], v[28:29], v[170:171]
	s_waitcnt vmcnt(0)
	v_pk_fma_f32 v[48:49], v[180:181], v[48:49], v[174:175]
	v_pk_fma_f32 v[46:47], v[182:183], v[46:47], v[172:173]
	v_pk_fma_f32 v[26:27], v[178:179], v[26:27], v[168:169]
	s_nop 0
	global_load_dwordx4 v[168:171], v[132:133], off offset:528 nt
	s_nop 0
	global_load_dwordx4 v[130:133], v[132:133], off offset:512 nt
	ds_read2_b32 v[172:173], v155 offset0:160 offset1:176
	s_waitcnt lgkmcnt(0)
	v_pk_mul_f32 v[14:15], v[14:15], v[172:173] op_sel_hi:[1,0]
	v_pk_mul_f32 v[16:17], v[16:17], v[172:173] op_sel_hi:[1,0]
	v_pk_mul_f32 v[10:11], v[10:11], v[172:173] op_sel_hi:[1,0]
	v_pk_mul_f32 v[12:13], v[12:13], v[172:173] op_sel_hi:[1,0]
	s_waitcnt vmcnt(1)
	v_pk_fma_f32 v[10:11], v[178:179], v[10:11], v[168:169]
	s_waitcnt vmcnt(0)
	v_pk_fma_f32 v[16:17], v[180:181], v[16:17], v[132:133]
	v_pk_fma_f32 v[14:15], v[182:183], v[14:15], v[130:131]
	global_load_dwordx4 v[130:133], v[136:137], off offset:528 nt
	s_nop 0
	global_load_dwordx4 v[134:137], v[136:137], off offset:512 nt
	v_mov_b32_e32 v168, v173
	v_pk_mul_f32 v[2:3], v[2:3], v[168:169] op_sel_hi:[1,0]
	v_pk_mul_f32 v[4:5], v[4:5], v[168:169] op_sel_hi:[1,0]
	v_pk_mul_f32 v[6:7], v[6:7], v[168:169] op_sel_hi:[1,0]
	v_pk_mul_f32 v[8:9], v[8:9], v[168:169] op_sel_hi:[1,0]
	v_pk_fma_f32 v[12:13], v[176:177], v[12:13], v[170:171]
	s_waitcnt vmcnt(1)
	v_pk_fma_f32 v[2:3], v[178:179], v[2:3], v[130:131]
	v_mul_f32_e32 v130, v123, v123
	v_mul_f32_e32 v131, v125, v125
	v_fmac_f32_e32 v130, v122, v122
	v_fmac_f32_e32 v131, v124, v124
	v_pk_fma_f32 v[4:5], v[176:177], v[4:5], v[132:133]
	v_add_f32_e32 v130, v130, v131
	v_mul_f32_e32 v131, v127, v127
	v_mul_f32_e32 v132, v129, v129
	v_fmac_f32_e32 v131, v126, v126
	v_fmac_f32_e32 v132, v128, v128
	v_add_f32_e32 v131, v131, v132
	v_add_f32_e32 v130, v130, v131
	v_mul_f32_e32 v131, v87, v87
	v_mul_f32_e32 v132, v89, v89
	v_fmac_f32_e32 v131, v86, v86
	v_fmac_f32_e32 v132, v88, v88
	v_add_f32_e32 v131, v131, v132
	v_add_f32_e32 v130, v130, v131
	v_mul_f32_e32 v131, v83, v83
	v_mul_f32_e32 v132, v85, v85
	v_fmac_f32_e32 v131, v82, v82
	v_fmac_f32_e32 v132, v84, v84
	v_add_f32_e32 v131, v131, v132
	v_add_f32_e32 v130, v131, v130
	v_mov_b32_e32 v131, v130
	s_nop 1
	v_permlane16_swap_b32_e32 v130, v131
	s_waitcnt vmcnt(0)
	v_pk_fma_f32 v[8:9], v[180:181], v[8:9], v[136:137]
	v_pk_fma_f32 v[6:7], v[182:183], v[6:7], v[134:135]
	s_waitcnt lgkmcnt(0)
	v_add_f32_e32 v130, v130, v131
	v_mov_b32_e32 v131, v130
	s_nop 1
	v_permlane32_swap_b32_e32 v130, v131
	s_and_saveexec_b64 s[82:83], s[6:7]
	s_cbranch_execz .LBB0_638
	s_waitcnt lgkmcnt(0)
	v_add_f32_e32 v130, v130, v131
	ds_write_b32 v159, v130
.LBB0_638:
	s_or_b64 exec, exec, s[82:83]
	v_mul_f32_e32 v130, v115, v115
	s_waitcnt lgkmcnt(0)
	v_mul_f32_e32 v131, v117, v117
	v_fmac_f32_e32 v130, v114, v114
	v_fmac_f32_e32 v131, v116, v116
	v_add_f32_e32 v130, v130, v131
	v_mul_f32_e32 v131, v119, v119
	v_mul_f32_e32 v132, v121, v121
	v_fmac_f32_e32 v131, v118, v118
	v_fmac_f32_e32 v132, v120, v120
	v_add_f32_e32 v131, v131, v132
	v_add_f32_e32 v130, v130, v131
	v_mul_f32_e32 v131, v91, v91
	v_mul_f32_e32 v132, v93, v93
	v_fmac_f32_e32 v131, v90, v90
	v_fmac_f32_e32 v132, v92, v92
	v_add_f32_e32 v131, v131, v132
	v_add_f32_e32 v130, v130, v131
	v_mul_f32_e32 v131, v107, v107
	v_mul_f32_e32 v132, v109, v109
	v_fmac_f32_e32 v131, v106, v106
	v_fmac_f32_e32 v132, v108, v108
	v_add_f32_e32 v131, v131, v132
	v_add_f32_e32 v130, v131, v130
	v_mov_b32_e32 v131, v130
	s_nop 1
	v_permlane16_swap_b32_e32 v130, v131
	s_waitcnt lgkmcnt(0)
	v_add_f32_e32 v130, v130, v131
	v_mov_b32_e32 v131, v130
	s_nop 1
	v_permlane32_swap_b32_e32 v130, v131
	s_and_saveexec_b64 s[82:83], s[6:7]
	s_cbranch_execz .LBB0_640
	s_waitcnt lgkmcnt(0)
	v_add_f32_e32 v130, v130, v131
	ds_write_b32 v159, v130 offset:256
.LBB0_640:
	s_or_b64 exec, exec, s[82:83]
	v_mul_f32_e32 v130, v35, v35
	s_waitcnt lgkmcnt(0)
	v_mul_f32_e32 v131, v37, v37
	v_fmac_f32_e32 v130, v34, v34
	v_fmac_f32_e32 v131, v36, v36
	v_add_f32_e32 v130, v130, v131
	v_mul_f32_e32 v131, v31, v31
	v_mul_f32_e32 v132, v33, v33
	v_fmac_f32_e32 v131, v30, v30
	v_fmac_f32_e32 v132, v32, v32
	v_add_f32_e32 v131, v131, v132
	v_add_f32_e32 v130, v130, v131
	v_mul_f32_e32 v131, v103, v103
	v_mul_f32_e32 v132, v105, v105
	v_fmac_f32_e32 v131, v102, v102
	v_fmac_f32_e32 v132, v104, v104
	v_add_f32_e32 v131, v131, v132
	v_add_f32_e32 v130, v130, v131
	v_mul_f32_e32 v131, v99, v99
	v_mul_f32_e32 v132, v101, v101
	v_fmac_f32_e32 v131, v98, v98
	v_fmac_f32_e32 v132, v100, v100
	v_add_f32_e32 v131, v131, v132
	v_add_f32_e32 v130, v131, v130
	v_mov_b32_e32 v131, v130
	s_nop 1
	v_permlane16_swap_b32_e32 v130, v131
	s_waitcnt lgkmcnt(0)
	v_add_f32_e32 v130, v130, v131
	v_mov_b32_e32 v131, v130
	s_nop 1
	v_permlane32_swap_b32_e32 v130, v131
	s_and_saveexec_b64 s[82:83], s[6:7]
	s_cbranch_execz .LBB0_642
	s_waitcnt lgkmcnt(0)
	v_add_f32_e32 v130, v130, v131
	ds_write_b32 v159, v130 offset:512
.LBB0_642:
	s_or_b64 exec, exec, s[82:83]
	v_mul_f32_e32 v130, v23, v23
	s_waitcnt lgkmcnt(0)
	v_mul_f32_e32 v131, v25, v25
	v_fmac_f32_e32 v130, v22, v22
	v_fmac_f32_e32 v131, v24, v24
	v_add_f32_e32 v130, v130, v131
	v_mul_f32_e32 v131, v19, v19
	v_mul_f32_e32 v132, v21, v21
	v_fmac_f32_e32 v131, v18, v18
	v_fmac_f32_e32 v132, v20, v20
	v_add_f32_e32 v131, v131, v132
	v_add_f32_e32 v130, v130, v131
	v_mul_f32_e32 v131, v79, v79
	v_mul_f32_e32 v132, v81, v81
	v_fmac_f32_e32 v131, v78, v78
	v_fmac_f32_e32 v132, v80, v80
	v_add_f32_e32 v131, v131, v132
	v_add_f32_e32 v130, v130, v131
	v_mul_f32_e32 v131, v75, v75
	v_mul_f32_e32 v132, v77, v77
	v_fmac_f32_e32 v131, v74, v74
	v_fmac_f32_e32 v132, v76, v76
	v_add_f32_e32 v131, v131, v132
	v_add_f32_e32 v130, v131, v130
	v_mov_b32_e32 v131, v130
	s_nop 1
	v_permlane16_swap_b32_e32 v130, v131
	s_waitcnt lgkmcnt(0)
	v_add_f32_e32 v130, v130, v131
	v_mov_b32_e32 v131, v130
	s_nop 1
	v_permlane32_swap_b32_e32 v130, v131
	s_and_saveexec_b64 s[82:83], s[6:7]
	s_cbranch_execz .LBB0_644
	s_waitcnt lgkmcnt(0)
	v_add_f32_e32 v130, v130, v131
	ds_write_b32 v159, v130 offset:768
.LBB0_644:
	s_or_b64 exec, exec, s[82:83]
	v_mul_f32_e32 v130, v43, v43
	s_waitcnt lgkmcnt(0)
	v_mul_f32_e32 v131, v45, v45
	v_fmac_f32_e32 v130, v42, v42
	v_fmac_f32_e32 v131, v44, v44
	v_add_f32_e32 v130, v130, v131
	v_mul_f32_e32 v131, v39, v39
	v_mul_f32_e32 v132, v41, v41
	v_fmac_f32_e32 v131, v38, v38
	v_fmac_f32_e32 v132, v40, v40
	v_add_f32_e32 v131, v131, v132
	v_add_f32_e32 v130, v130, v131
	v_mul_f32_e32 v131, v55, v55
	v_mul_f32_e32 v132, v57, v57
	v_fmac_f32_e32 v131, v54, v54
	v_fmac_f32_e32 v132, v56, v56
	v_add_f32_e32 v131, v131, v132
	v_add_f32_e32 v130, v130, v131
	v_mul_f32_e32 v131, v51, v51
	v_mul_f32_e32 v132, v53, v53
	v_fmac_f32_e32 v131, v50, v50
	v_fmac_f32_e32 v132, v52, v52
	v_add_f32_e32 v131, v131, v132
	v_add_f32_e32 v130, v131, v130
	v_mov_b32_e32 v131, v130
	s_nop 1
	v_permlane16_swap_b32_e32 v130, v131
	s_waitcnt lgkmcnt(0)
	v_add_f32_e32 v130, v130, v131
	v_mov_b32_e32 v131, v130
	s_nop 1
	v_permlane32_swap_b32_e32 v130, v131
	s_and_saveexec_b64 s[82:83], s[6:7]
	s_cbranch_execz .LBB0_646
	s_waitcnt lgkmcnt(0)
	v_add_f32_e32 v130, v130, v131
	ds_write_b32 v159, v130 offset:2048
.LBB0_646:
	s_or_b64 exec, exec, s[82:83]
	v_mul_f32_e32 v130, v63, v63
	s_waitcnt lgkmcnt(0)
	v_mul_f32_e32 v131, v65, v65
	v_fmac_f32_e32 v130, v62, v62
	v_fmac_f32_e32 v131, v64, v64
	v_add_f32_e32 v130, v130, v131
	v_mul_f32_e32 v131, v59, v59
	v_mul_f32_e32 v132, v61, v61
	v_fmac_f32_e32 v131, v58, v58
	v_fmac_f32_e32 v132, v60, v60
	v_add_f32_e32 v131, v131, v132
	v_add_f32_e32 v130, v130, v131
	v_mul_f32_e32 v131, v47, v47
	v_mul_f32_e32 v132, v49, v49
	v_fmac_f32_e32 v131, v46, v46
	v_fmac_f32_e32 v132, v48, v48
	v_add_f32_e32 v131, v131, v132
	v_add_f32_e32 v130, v130, v131
	v_mul_f32_e32 v131, v27, v27
	v_mul_f32_e32 v132, v29, v29
	v_fmac_f32_e32 v131, v26, v26
	v_fmac_f32_e32 v132, v28, v28
	v_add_f32_e32 v131, v131, v132
	v_add_f32_e32 v130, v131, v130
	v_mov_b32_e32 v131, v130
	s_nop 1
	v_permlane16_swap_b32_e32 v130, v131
	s_waitcnt lgkmcnt(0)
	v_add_f32_e32 v130, v130, v131
	v_mov_b32_e32 v131, v130
	s_nop 1
	v_permlane32_swap_b32_e32 v130, v131
	s_and_saveexec_b64 s[82:83], s[6:7]
	s_cbranch_execz .LBB0_648
	s_waitcnt lgkmcnt(0)
	v_add_f32_e32 v130, v130, v131
	ds_write_b32 v159, v130 offset:2304
.LBB0_648:
	s_or_b64 exec, exec, s[82:83]
	v_mul_f32_e32 v130, v71, v71
	s_waitcnt lgkmcnt(0)
	v_mul_f32_e32 v131, v73, v73
	v_fmac_f32_e32 v130, v70, v70
	v_fmac_f32_e32 v131, v72, v72
	v_add_f32_e32 v130, v130, v131
	v_mul_f32_e32 v131, v67, v67
	v_mul_f32_e32 v132, v69, v69
	v_fmac_f32_e32 v131, v66, v66
	v_fmac_f32_e32 v132, v68, v68
	v_add_f32_e32 v131, v131, v132
	v_add_f32_e32 v130, v130, v131
	v_mul_f32_e32 v131, v15, v15
	v_mul_f32_e32 v132, v17, v17
	v_fmac_f32_e32 v131, v14, v14
	v_fmac_f32_e32 v132, v16, v16
	v_add_f32_e32 v131, v131, v132
	v_add_f32_e32 v130, v130, v131
	v_mul_f32_e32 v131, v11, v11
	v_mul_f32_e32 v132, v13, v13
	v_fmac_f32_e32 v131, v10, v10
	v_fmac_f32_e32 v132, v12, v12
	v_add_f32_e32 v131, v131, v132
	v_add_f32_e32 v130, v131, v130
	v_mov_b32_e32 v131, v130
	s_nop 1
	v_permlane16_swap_b32_e32 v130, v131
	s_waitcnt lgkmcnt(0)
	v_add_f32_e32 v130, v130, v131
	v_mov_b32_e32 v131, v130
	s_nop 1
	v_permlane32_swap_b32_e32 v130, v131
	s_and_saveexec_b64 s[82:83], s[6:7]
	s_cbranch_execz .LBB0_650
	s_waitcnt lgkmcnt(0)
	v_add_f32_e32 v130, v130, v131
	ds_write_b32 v159, v130 offset:2560
.LBB0_650:
	s_or_b64 exec, exec, s[82:83]
	v_mul_f32_e32 v130, v95, v95
	s_waitcnt lgkmcnt(0)
	v_mul_f32_e32 v131, v97, v97
	v_fmac_f32_e32 v130, v94, v94
	v_fmac_f32_e32 v131, v96, v96
	v_add_f32_e32 v130, v130, v131
	v_mul_f32_e32 v131, v111, v111
	v_mul_f32_e32 v132, v113, v113
	v_fmac_f32_e32 v131, v110, v110
	v_fmac_f32_e32 v132, v112, v112
	v_add_f32_e32 v131, v131, v132
	v_add_f32_e32 v130, v130, v131
	v_mul_f32_e32 v131, v7, v7
	v_mul_f32_e32 v132, v9, v9
	v_fmac_f32_e32 v131, v6, v6
	v_fmac_f32_e32 v132, v8, v8
	v_add_f32_e32 v131, v131, v132
	v_add_f32_e32 v130, v130, v131
	v_mul_f32_e32 v131, v3, v3
	v_mul_f32_e32 v132, v5, v5
	v_fmac_f32_e32 v131, v2, v2
	v_fmac_f32_e32 v132, v4, v4
	v_add_f32_e32 v131, v131, v132
	v_add_f32_e32 v130, v131, v130
	v_mov_b32_e32 v131, v130
	s_nop 1
	v_permlane16_swap_b32_e32 v130, v131
	s_waitcnt lgkmcnt(0)
	v_add_f32_e32 v130, v130, v131
	v_mov_b32_e32 v131, v130
	s_nop 1
	v_permlane32_swap_b32_e32 v130, v131
	s_and_saveexec_b64 s[82:83], s[6:7]
	s_cbranch_execz .LBB0_652
	s_waitcnt lgkmcnt(0)
	v_add_f32_e32 v130, v130, v131
	ds_write_b32 v159, v130 offset:2816

.LBB0_968:
	v_mul_f32_e32 v140, v125, v125
	v_mul_f32_e32 v141, v127, v127
	v_fmac_f32_e32 v140, v124, v124
	v_fmac_f32_e32 v141, v126, v126
	v_add_f32_e32 v140, v140, v141
	v_mul_f32_e32 v141, v121, v121
	v_mul_f32_e32 v142, v123, v123
	v_fmac_f32_e32 v141, v120, v120
	v_fmac_f32_e32 v142, v122, v122
	v_add_f32_e32 v141, v141, v142
	v_add_f32_e32 v140, v140, v141
	v_mul_f32_e32 v141, v61, v61
	v_mul_f32_e32 v142, v63, v63
	v_fmac_f32_e32 v141, v60, v60
	v_fmac_f32_e32 v142, v62, v62
	v_and_b32_e32 v137, 64, v158
	v_add_f32_e32 v141, v141, v142
	v_xor_b32_e32 v136, 16, v158
	v_add_u32_e32 v137, 64, v137
	v_add_f32_e32 v140, v140, v141
	v_mul_f32_e32 v141, v57, v57
	v_mul_f32_e32 v142, v59, v59
	v_cmp_lt_i32_e32 vcc, v136, v137
	v_fmac_f32_e32 v141, v56, v56
	v_fmac_f32_e32 v142, v58, v58
	v_cndmask_b32_e32 v136, v158, v136, vcc
	v_add_f32_e32 v141, v141, v142
	v_lshlrev_b32_e32 v136, 2, v136
	v_add_f32_e32 v141, v140, v141
	v_mov_b32_e32 v142, v141
	s_nop 1
	v_permlane16_swap_b32_e32 v141, v142
	v_xor_b32_e32 v140, 32, v158
	v_cmp_lt_i32_e32 vcc, v140, v137
	s_waitcnt lgkmcnt(0)
	v_add_f32_e32 v141, v141, v142
	v_cndmask_b32_e32 v137, v158, v140, vcc
	v_lshlrev_b32_e32 v140, 2, v137
	v_mov_b32_e32 v142, v141
	s_nop 1
	v_permlane32_swap_b32_e32 v141, v142
	v_cmp_eq_u32_e32 vcc, 0, v139
	v_lshl_add_u32 v137, v138, 4, s67
	s_and_saveexec_b64 s[4:5], vcc
	s_cbranch_execz .LBB0_970
	s_waitcnt lgkmcnt(0)
	v_add_f32_e32 v141, v141, v142
	ds_write_b32 v137, v141
.LBB0_970:
	s_or_b64 exec, exec, s[4:5]
	v_mul_f32_e32 v141, v117, v117
	s_waitcnt lgkmcnt(0)
	v_mul_f32_e32 v142, v119, v119
	v_fmac_f32_e32 v141, v116, v116
	v_fmac_f32_e32 v142, v118, v118
	v_add_f32_e32 v141, v141, v142
	v_mul_f32_e32 v142, v113, v113
	v_mul_f32_e32 v143, v115, v115
	v_fmac_f32_e32 v142, v112, v112
	v_fmac_f32_e32 v143, v114, v114
	v_add_f32_e32 v142, v142, v143
	v_add_f32_e32 v141, v141, v142
	v_mul_f32_e32 v142, v53, v53
	v_mul_f32_e32 v143, v55, v55
	v_fmac_f32_e32 v142, v52, v52
	v_fmac_f32_e32 v143, v54, v54
	v_add_f32_e32 v142, v142, v143
	v_add_f32_e32 v141, v141, v142
	v_mul_f32_e32 v142, v49, v49
	v_mul_f32_e32 v143, v51, v51
	v_fmac_f32_e32 v142, v48, v48
	v_fmac_f32_e32 v143, v50, v50
	v_add_f32_e32 v142, v142, v143
	v_add_f32_e32 v141, v141, v142
	v_mov_b32_e32 v142, v141
	s_nop 1
	v_permlane16_swap_b32_e32 v141, v142
	s_waitcnt lgkmcnt(0)
	v_add_f32_e32 v141, v141, v142
	v_mov_b32_e32 v142, v141
	s_nop 1
	v_permlane32_swap_b32_e32 v141, v142
	s_and_saveexec_b64 s[4:5], vcc
	s_cbranch_execz .LBB0_972
	s_waitcnt lgkmcnt(0)
	v_add_f32_e32 v141, v141, v142
	ds_write_b32 v137, v141 offset:256
.LBB0_972:
	s_or_b64 exec, exec, s[4:5]
	v_mul_f32_e32 v141, v109, v109
	s_waitcnt lgkmcnt(0)
	v_mul_f32_e32 v142, v111, v111
	v_fmac_f32_e32 v141, v108, v108
	v_fmac_f32_e32 v142, v110, v110
	v_add_f32_e32 v141, v141, v142
	v_mul_f32_e32 v142, v105, v105
	v_mul_f32_e32 v143, v107, v107
	v_fmac_f32_e32 v142, v104, v104
	v_fmac_f32_e32 v143, v106, v106
	v_add_f32_e32 v142, v142, v143
	v_add_f32_e32 v141, v141, v142
	v_mul_f32_e32 v142, v45, v45
	v_mul_f32_e32 v143, v47, v47
	v_fmac_f32_e32 v142, v44, v44
	v_fmac_f32_e32 v143, v46, v46
	v_add_f32_e32 v142, v142, v143
	v_add_f32_e32 v141, v141, v142
	v_mul_f32_e32 v142, v41, v41
	v_mul_f32_e32 v143, v43, v43
	v_fmac_f32_e32 v142, v40, v40
	v_fmac_f32_e32 v143, v42, v42
	v_add_f32_e32 v142, v142, v143
	v_add_f32_e32 v141, v141, v142
	v_mov_b32_e32 v142, v141
	s_nop 1
	v_permlane16_swap_b32_e32 v141, v142
	s_waitcnt lgkmcnt(0)
	v_add_f32_e32 v141, v141, v142
	v_mov_b32_e32 v142, v141
	s_nop 1
	v_permlane32_swap_b32_e32 v141, v142
	s_and_saveexec_b64 s[4:5], vcc
	s_cbranch_execz .LBB0_974
	s_waitcnt lgkmcnt(0)
	v_add_f32_e32 v141, v141, v142
	ds_write_b32 v137, v141 offset:512
.LBB0_974:
	s_or_b64 exec, exec, s[4:5]
	v_mul_f32_e32 v141, v101, v101
	s_waitcnt lgkmcnt(0)
	v_mul_f32_e32 v142, v103, v103
	v_fmac_f32_e32 v141, v100, v100
	v_fmac_f32_e32 v142, v102, v102
	v_add_f32_e32 v141, v141, v142
	v_mul_f32_e32 v142, v97, v97
	v_mul_f32_e32 v143, v99, v99
	v_fmac_f32_e32 v142, v96, v96
	v_fmac_f32_e32 v143, v98, v98
	v_add_f32_e32 v142, v142, v143
	v_add_f32_e32 v141, v141, v142
	v_mul_f32_e32 v142, v37, v37
	v_mul_f32_e32 v143, v39, v39
	v_fmac_f32_e32 v142, v36, v36
	v_fmac_f32_e32 v143, v38, v38
	v_add_f32_e32 v142, v142, v143
	v_add_f32_e32 v141, v141, v142
	v_mul_f32_e32 v142, v33, v33
	v_mul_f32_e32 v143, v35, v35
	v_fmac_f32_e32 v142, v32, v32
	v_fmac_f32_e32 v143, v34, v34
	v_add_f32_e32 v142, v142, v143
	v_add_f32_e32 v141, v141, v142
	v_mov_b32_e32 v142, v141
	s_nop 1
	v_permlane16_swap_b32_e32 v141, v142
	s_waitcnt lgkmcnt(0)
	v_add_f32_e32 v141, v141, v142
	v_mov_b32_e32 v142, v141
	s_nop 1
	v_permlane32_swap_b32_e32 v141, v142
	s_and_saveexec_b64 s[4:5], vcc
	s_cbranch_execz .LBB0_976
	s_waitcnt lgkmcnt(0)
	v_add_f32_e32 v141, v141, v142
	ds_write_b32 v137, v141 offset:768
.LBB0_976:
	s_or_b64 exec, exec, s[4:5]
	v_mul_f32_e32 v141, v93, v93
	s_waitcnt lgkmcnt(0)
	v_mul_f32_e32 v142, v95, v95
	v_fmac_f32_e32 v141, v92, v92
	v_fmac_f32_e32 v142, v94, v94
	v_add_f32_e32 v141, v141, v142
	v_mul_f32_e32 v142, v89, v89
	v_mul_f32_e32 v143, v91, v91
	v_fmac_f32_e32 v142, v88, v88
	v_fmac_f32_e32 v143, v90, v90
	v_add_f32_e32 v142, v142, v143
	v_add_f32_e32 v141, v141, v142
	v_mul_f32_e32 v142, v29, v29
	v_mul_f32_e32 v143, v31, v31
	v_fmac_f32_e32 v142, v28, v28
	v_fmac_f32_e32 v143, v30, v30
	v_add_f32_e32 v142, v142, v143
	v_add_f32_e32 v141, v141, v142
	v_mul_f32_e32 v142, v25, v25
	v_mul_f32_e32 v143, v27, v27
	v_fmac_f32_e32 v142, v24, v24
	v_fmac_f32_e32 v143, v26, v26
	v_add_f32_e32 v142, v142, v143
	v_add_f32_e32 v141, v141, v142
	v_mov_b32_e32 v142, v141
	s_nop 1
	v_permlane16_swap_b32_e32 v141, v142
	s_waitcnt lgkmcnt(0)
	v_add_f32_e32 v141, v141, v142
	v_mov_b32_e32 v142, v141
	s_nop 1
	v_permlane32_swap_b32_e32 v141, v142
	s_and_saveexec_b64 s[4:5], vcc
	s_cbranch_execz .LBB0_978
	s_waitcnt lgkmcnt(0)
	v_add_f32_e32 v141, v141, v142
	ds_write_b32 v137, v141 offset:2048
.LBB0_978:
	s_or_b64 exec, exec, s[4:5]
	v_mul_f32_e32 v141, v85, v85
	s_waitcnt lgkmcnt(0)
	v_mul_f32_e32 v142, v87, v87
	v_fmac_f32_e32 v141, v84, v84
	v_fmac_f32_e32 v142, v86, v86
	v_add_f32_e32 v141, v141, v142
	v_mul_f32_e32 v142, v81, v81
	v_mul_f32_e32 v143, v83, v83
	v_fmac_f32_e32 v142, v80, v80
	v_fmac_f32_e32 v143, v82, v82
	v_add_f32_e32 v142, v142, v143
	v_add_f32_e32 v141, v141, v142
	v_mul_f32_e32 v142, v21, v21
	v_mul_f32_e32 v143, v23, v23
	v_fmac_f32_e32 v142, v20, v20
	v_fmac_f32_e32 v143, v22, v22
	v_add_f32_e32 v142, v142, v143
	v_add_f32_e32 v141, v141, v142
	v_mul_f32_e32 v142, v17, v17
	v_mul_f32_e32 v143, v19, v19
	v_fmac_f32_e32 v142, v16, v16
	v_fmac_f32_e32 v143, v18, v18
	v_add_f32_e32 v142, v142, v143
	v_add_f32_e32 v141, v141, v142
	v_mov_b32_e32 v142, v141
	s_nop 1
	v_permlane16_swap_b32_e32 v141, v142
	s_waitcnt lgkmcnt(0)
	v_add_f32_e32 v141, v141, v142
	v_mov_b32_e32 v142, v141
	s_nop 1
	v_permlane32_swap_b32_e32 v141, v142
	s_and_saveexec_b64 s[4:5], vcc
	s_cbranch_execz .LBB0_980
	s_waitcnt lgkmcnt(0)
	v_add_f32_e32 v141, v141, v142
	ds_write_b32 v137, v141 offset:2304
.LBB0_980:
	s_or_b64 exec, exec, s[4:5]
	v_mul_f32_e32 v141, v77, v77
	s_waitcnt lgkmcnt(0)
	v_mul_f32_e32 v142, v79, v79
	v_fmac_f32_e32 v141, v76, v76
	v_fmac_f32_e32 v142, v78, v78
	v_add_f32_e32 v141, v141, v142
	v_mul_f32_e32 v142, v73, v73
	v_mul_f32_e32 v143, v75, v75
	v_fmac_f32_e32 v142, v72, v72
	v_fmac_f32_e32 v143, v74, v74
	v_add_f32_e32 v142, v142, v143
	v_add_f32_e32 v141, v141, v142
	v_mul_f32_e32 v142, v13, v13
	v_mul_f32_e32 v143, v15, v15
	v_fmac_f32_e32 v142, v12, v12
	v_fmac_f32_e32 v143, v14, v14
	v_add_f32_e32 v142, v142, v143
	v_add_f32_e32 v141, v141, v142
	v_mul_f32_e32 v142, v9, v9
	v_mul_f32_e32 v143, v11, v11
	v_fmac_f32_e32 v142, v8, v8
	v_fmac_f32_e32 v143, v10, v10
	v_add_f32_e32 v142, v142, v143
	v_add_f32_e32 v141, v141, v142
	v_mov_b32_e32 v142, v141
	s_nop 1
	v_permlane16_swap_b32_e32 v141, v142
	s_waitcnt lgkmcnt(0)
	v_add_f32_e32 v141, v141, v142
	v_mov_b32_e32 v142, v141
	s_nop 1
	v_permlane32_swap_b32_e32 v141, v142
	s_and_saveexec_b64 s[4:5], vcc
	s_cbranch_execz .LBB0_982
	s_waitcnt lgkmcnt(0)
	v_add_f32_e32 v141, v141, v142
	ds_write_b32 v137, v141 offset:2560
.LBB0_982:
	s_or_b64 exec, exec, s[4:5]
	v_mul_f32_e32 v141, v69, v69
	s_waitcnt lgkmcnt(0)
	v_mul_f32_e32 v142, v71, v71
	v_fmac_f32_e32 v141, v68, v68
	v_fmac_f32_e32 v142, v70, v70
	v_add_f32_e32 v141, v141, v142
	v_mul_f32_e32 v142, v65, v65
	v_mul_f32_e32 v143, v67, v67
	v_fmac_f32_e32 v142, v64, v64
	v_fmac_f32_e32 v143, v66, v66
	v_add_f32_e32 v142, v142, v143
	v_add_f32_e32 v141, v141, v142
	v_mul_f32_e32 v142, v5, v5
	v_mul_f32_e32 v143, v7, v7
	v_fmac_f32_e32 v142, v4, v4
	v_fmac_f32_e32 v143, v6, v6
	v_add_f32_e32 v142, v142, v143
	v_add_f32_e32 v141, v141, v142
	v_mul_f32_e32 v142, v1, v1
	v_mul_f32_e32 v143, v3, v3
	v_fmac_f32_e32 v142, v0, v0
	v_fmac_f32_e32 v143, v2, v2
	v_add_f32_e32 v142, v142, v143
	v_add_f32_e32 v141, v141, v142
	v_mov_b32_e32 v136, v141
	s_nop 1
	v_permlane16_swap_b32_e32 v141, v136
	s_waitcnt lgkmcnt(0)
	v_add_f32_e32 v136, v141, v136
	v_mov_b32_e32 v140, v136
	s_nop 1
	v_permlane32_swap_b32_e32 v136, v140
	s_and_saveexec_b64 s[4:5], vcc
	s_cbranch_execz .LBB0_984
	s_waitcnt lgkmcnt(0)
	v_add_f32_e32 v136, v136, v140
	ds_write_b32 v137, v136 offset:2816
